# P8 post-mix rmsnorm+residual loop hand-rewritten: gains hoisted, double-buffered row prefetch, no serialized load/store chain
# baseline (speedup 1.0000x reference)
; #define PH_ON(k) if constexpr (((PH_MASK) >> (k)) & 1)
; __device__ __forceinline__ unsigned pk2(float lo, float hi) { const f32x2_h v = {lo, hi}; return __builtin_bit_cast(unsigned, __builtin_convertvector(v, bf16x2_h)); }
; __global__ void __launch_bounds__(512, 2) fwd_megakernel(Params p) {
;     ...
;     PH_ON(8) {
;         const float* gpo = p.in[21];
;         for (int m = gw; m < MROWS; m += NGW) {
;             const u32x2* r8 = (const u32x2*)(MB + (size_t)m * DM) + lane; const f32x4* xr = (const f32x4*)xrow_ptr(p, m) + lane; f32x4 v[8]; float s = 0.f;
; #pragma unroll
;             for (int j = 0; j < 8; ++j) { const u32x2 w = r8[64 * j]; v[j] = (f32x4){__uint_as_float(w.x << 16), __uint_as_float(w.x & 0xffff0000u), __uint_as_float(w.y << 16), __uint_as_float(w.y & 0xffff0000u)};
;                 s += (v[j].x * v[j].x + v[j].y * v[j].y) + (v[j].z * v[j].z + v[j].w * v[j].w); }
;             const float rm = 1.f / sqrtf(wave_sum(s) * (1.f / DM) + RMS_EPS); float s1 = 0.f;
;             u32x2* h8 = (u32x2*)(Hb + (size_t)m * DM) + lane;
; #pragma unroll
;             for (int j = 0; j < 8; ++j) { const f32x4 gg = *(const f32x4*)(gpo + 4 * lane + 256 * j); v[j] = xr[64 * j] + v[j] * rm * gg;
;                 s1 += (v[j].x * v[j].x + v[j].y * v[j].y) + (v[j].z * v[j].z + v[j].w * v[j].w);
;                 u32x2 o; o.x = pk2(v[j].x, v[j].y); o.y = pk2(v[j].z, v[j].w); h8[64 * j] = o; }
;             s1 = wave_sum(s1);
;             if (lane == 0) rsq_x[m] = s1;
;         }
;     }
.LBB0_830:
	s_or_b64 exec, exec, s[0:1]
	v_readlane_b32 s4, v246, 51
	v_readlane_b32 s5, v246, 52
	s_andn2_b64 vcc, exec, s[4:5]
	v_xor_b32_e32 v134, 32, v170
	s_waitcnt lgkmcnt(0)
	v_cndmask_b32_e64 v0, 0, 1, s[4:5]
	v_cmp_ne_u32_e64 s[0:1], 1, v0
	s_barrier
	s_cbranch_vccnz .LBB0_835
	v_cmp_lt_i32_e32 vcc, v134, v145
	v_readlane_b32 s36, v246, 9
	v_readlane_b32 s37, v246, 10
	v_cndmask_b32_e32 v0, v170, v134, vcc
	v_lshlrev_b32_e32 v32, 2, v0
	v_readlane_b32 s38, v246, 11
	v_readlane_b32 s39, v246, 12
	v_readlane_b32 s46, v246, 35
	v_readlane_b32 s47, v246, 36
	v_mov_b32_e32 v33, 0x358637bd
	v_mov_b32_e32 v34, 0x260
	v_mov_b32_e32 v35, 0
	v_cmp_eq_u32_e64 s[4:5], 0, v169
	s_mov_b32 s10, 0xf800000
	s_mov_b32 s14, s60
	s_add_u32 s48, s46, 0x1000
	s_addc_u32 s49, s47, 0
	s_add_u32 s40, s76, 0xa100000
	s_addc_u32 s41, s77, 0
	s_add_u32 s42, s76, 0x1a000000
	s_addc_u32 s43, s77, 0
	s_add_u32 s44, s76, 0xa0000
	s_addc_u32 s45, s77, 0
	global_load_dwordx4 v[208:211], v164, s[46:47]
	global_load_dwordx4 v[212:215], v164, s[46:47] offset:1024
	global_load_dwordx4 v[216:219], v164, s[46:47] offset:2048
	global_load_dwordx4 v[220:223], v164, s[46:47] offset:3072
	global_load_dwordx4 v[224:227], v164, s[48:49]
	global_load_dwordx4 v[228:231], v164, s[48:49] offset:1024
	global_load_dwordx4 v[232:235], v164, s[48:49] offset:2048
	global_load_dwordx4 v[236:239], v164, s[48:49] offset:3072
	s_ashr_i32 s7, s14, 31
	s_mov_b32 s6, s14
	s_lshl_b64 s[8:9], s[6:7], 12
	s_add_u32 s16, s40, s8
	s_addc_u32 s17, s41, s9
	s_add_i32 s8, s14, 0xffffe000
	s_cmpk_lt_i32 s14, 0x2000
	s_cselect_b32 s8, s14, s8
	s_cselect_b32 s18, s36, s38
	s_cselect_b32 s19, s37, s39
	s_ashr_i32 s9, s8, 31
	s_lshl_b64 s[8:9], s[8:9], 13
	s_add_u32 s18, s18, s8
	s_addc_u32 s19, s19, s9
	s_add_u32 s20, s18, 0x1000
	s_addc_u32 s21, s19, 0
	global_load_dwordx2 v[40:41], v162, s[16:17]
	global_load_dwordx2 v[42:43], v162, s[16:17] offset:512
	global_load_dwordx2 v[44:45], v162, s[16:17] offset:1024
	global_load_dwordx2 v[46:47], v162, s[16:17] offset:1536
	global_load_dwordx2 v[48:49], v162, s[16:17] offset:2048
	global_load_dwordx2 v[50:51], v162, s[16:17] offset:2560
	global_load_dwordx2 v[52:53], v162, s[16:17] offset:3072
	global_load_dwordx2 v[54:55], v162, s[16:17] offset:3584
	global_load_dwordx4 v[72:75], v160, s[18:19]
	global_load_dwordx4 v[76:79], v160, s[18:19] offset:1024
	global_load_dwordx4 v[80:83], v160, s[18:19] offset:2048
	global_load_dwordx4 v[84:87], v160, s[18:19] offset:3072
	global_load_dwordx4 v[88:91], v160, s[20:21]
	global_load_dwordx4 v[92:95], v160, s[20:21] offset:1024
	global_load_dwordx4 v[96:99], v160, s[20:21] offset:2048
	global_load_dwordx4 v[100:103], v160, s[20:21] offset:3072
	s_waitcnt vmcnt(0)
	s_branch .Lp8_entryA
.Lp8_topA:
	s_waitcnt vmcnt(9)
.Lp8_entryA:
	v_lshlrev_b32_e32 v0, 16, v40
	v_and_b32_e32 v1, 0xffff0000, v40
	v_lshlrev_b32_e32 v2, 16, v41
	v_and_b32_e32 v3, 0xffff0000, v41
	v_lshlrev_b32_e32 v4, 16, v42
	v_and_b32_e32 v5, 0xffff0000, v42
	v_lshlrev_b32_e32 v6, 16, v43
	v_and_b32_e32 v7, 0xffff0000, v43
	v_lshlrev_b32_e32 v8, 16, v44
	v_and_b32_e32 v9, 0xffff0000, v44
	v_lshlrev_b32_e32 v10, 16, v45
	v_and_b32_e32 v11, 0xffff0000, v45
	v_lshlrev_b32_e32 v12, 16, v46
	v_and_b32_e32 v13, 0xffff0000, v46
	v_lshlrev_b32_e32 v14, 16, v47
	v_and_b32_e32 v15, 0xffff0000, v47
	v_lshlrev_b32_e32 v16, 16, v48
	v_and_b32_e32 v17, 0xffff0000, v48
	v_lshlrev_b32_e32 v18, 16, v49
	v_and_b32_e32 v19, 0xffff0000, v49
	v_lshlrev_b32_e32 v20, 16, v50
	v_and_b32_e32 v21, 0xffff0000, v50
	v_lshlrev_b32_e32 v22, 16, v51
	v_and_b32_e32 v23, 0xffff0000, v51
	v_lshlrev_b32_e32 v24, 16, v52
	v_and_b32_e32 v25, 0xffff0000, v52
	v_lshlrev_b32_e32 v26, 16, v53
	v_and_b32_e32 v27, 0xffff0000, v53
	v_lshlrev_b32_e32 v28, 16, v54
	v_and_b32_e32 v29, 0xffff0000, v54
	v_lshlrev_b32_e32 v30, 16, v55
	v_and_b32_e32 v31, 0xffff0000, v55
	s_ashr_i32 s15, s14, 31
	s_lshl_b64 s[8:9], s[14:15], 12
	s_add_u32 s24, s42, s8
	s_addc_u32 s25, s43, s9
	s_lshl_b64 s[8:9], s[14:15], 2
	s_add_u32 s26, s44, s8
	s_addc_u32 s27, s45, s9
	s_add_i32 s14, s14, s62
	s_cmpk_gt_i32 s14, 0x5fff
	s_cbranch_scc1 .Lp8_nopfA
	s_ashr_i32 s7, s14, 31
	s_mov_b32 s6, s14
	s_lshl_b64 s[8:9], s[6:7], 12
	s_add_u32 s16, s40, s8
	s_addc_u32 s17, s41, s9
	s_add_i32 s8, s14, 0xffffe000
	s_cmpk_lt_i32 s14, 0x2000
	s_cselect_b32 s8, s14, s8
	s_cselect_b32 s18, s36, s38
	s_cselect_b32 s19, s37, s39
	s_ashr_i32 s9, s8, 31
	s_lshl_b64 s[8:9], s[8:9], 13
	s_add_u32 s18, s18, s8
	s_addc_u32 s19, s19, s9
	s_add_u32 s20, s18, 0x1000
	s_addc_u32 s21, s19, 0
	global_load_dwordx2 v[56:57], v162, s[16:17]
	global_load_dwordx2 v[58:59], v162, s[16:17] offset:512
	global_load_dwordx2 v[60:61], v162, s[16:17] offset:1024
	global_load_dwordx2 v[62:63], v162, s[16:17] offset:1536
	global_load_dwordx2 v[64:65], v162, s[16:17] offset:2048
	global_load_dwordx2 v[66:67], v162, s[16:17] offset:2560
	global_load_dwordx2 v[68:69], v162, s[16:17] offset:3072
	global_load_dwordx2 v[70:71], v162, s[16:17] offset:3584
	global_load_dwordx4 v[172:175], v160, s[18:19]
	global_load_dwordx4 v[176:179], v160, s[18:19] offset:1024
	global_load_dwordx4 v[180:183], v160, s[18:19] offset:2048
	global_load_dwordx4 v[184:187], v160, s[18:19] offset:3072
	global_load_dwordx4 v[188:191], v160, s[20:21]
	global_load_dwordx4 v[192:195], v160, s[20:21] offset:1024
	global_load_dwordx4 v[196:199], v160, s[20:21] offset:2048
	global_load_dwordx4 v[200:203], v160, s[20:21] offset:3072
; __device__ __forceinline__ unsigned pk2(float lo, float hi) { const f32x2_h v = {lo, hi}; return __builtin_bit_cast(unsigned, __builtin_convertvector(v, bf16x2_h)); }
; __device__ __forceinline__ float wave_sum(float v) {
; #pragma unroll
;     for (int o = 1; o < 64; o <<= 1) v += __shfl_xor(v, o);
;     return v;
; }
; __global__ void __launch_bounds__(512, 2) fwd_megakernel(Params p) {
;     ...
;             const u32x2* r8 = (const u32x2*)(MB + (size_t)m * DM) + lane; const f32x4* xr = (const f32x4*)xrow_ptr(p, m) + lane; f32x4 v[8]; float s = 0.f;
; #pragma unroll
;             for (int j = 0; j < 8; ++j) { const u32x2 w = r8[64 * j]; v[j] = (f32x4){__uint_as_float(w.x << 16), __uint_as_float(w.x & 0xffff0000u), __uint_as_float(w.y << 16), __uint_as_float(w.y & 0xffff0000u)};
;                 s += (v[j].x * v[j].x + v[j].y * v[j].y) + (v[j].z * v[j].z + v[j].w * v[j].w); }
;             const float rm = 1.f / sqrtf(wave_sum(s) * (1.f / DM) + RMS_EPS); float s1 = 0.f;
;             u32x2* h8 = (u32x2*)(Hb + (size_t)m * DM) + lane;
; #pragma unroll
;             for (int j = 0; j < 8; ++j) { const f32x4 gg = *(const f32x4*)(gpo + 4 * lane + 256 * j); v[j] = xr[64 * j] + v[j] * rm * gg;
;                 s1 += (v[j].x * v[j].x + v[j].y * v[j].y) + (v[j].z * v[j].z + v[j].w * v[j].w);
;                 u32x2 o; o.x = pk2(v[j].x, v[j].y); o.y = pk2(v[j].z, v[j].w); h8[64 * j] = o; }
;             s1 = wave_sum(s1);
.Lp8_nopfA:
	v_pk_mul_f32 v[146:147], v[0:1], v[0:1]
	v_pk_mul_f32 v[148:149], v[2:3], v[2:3]
	v_pk_fma_f32 v[146:147], v[4:5], v[4:5], v[146:147]
	v_pk_fma_f32 v[148:149], v[6:7], v[6:7], v[148:149]
	v_pk_fma_f32 v[146:147], v[8:9], v[8:9], v[146:147]
	v_pk_fma_f32 v[148:149], v[10:11], v[10:11], v[148:149]
	v_pk_fma_f32 v[146:147], v[12:13], v[12:13], v[146:147]
	v_pk_fma_f32 v[148:149], v[14:15], v[14:15], v[148:149]
	v_pk_fma_f32 v[146:147], v[16:17], v[16:17], v[146:147]
	v_pk_fma_f32 v[148:149], v[18:19], v[18:19], v[148:149]
	v_pk_fma_f32 v[146:147], v[20:21], v[20:21], v[146:147]
	v_pk_fma_f32 v[148:149], v[22:23], v[22:23], v[148:149]
	v_pk_fma_f32 v[146:147], v[24:25], v[24:25], v[146:147]
	v_pk_fma_f32 v[148:149], v[26:27], v[26:27], v[148:149]
	v_pk_fma_f32 v[146:147], v[28:29], v[28:29], v[146:147]
	v_pk_fma_f32 v[148:149], v[30:31], v[30:31], v[148:149]
	s_nop 0
	v_pk_add_f32 v[146:147], v[146:147], v[148:149]
	s_nop 0
	v_add_f32_e32 v150, v146, v147
	ds_bpermute_b32 v151, v140, v150
	s_waitcnt lgkmcnt(0)
	v_add_f32_e32 v150, v150, v151
	ds_bpermute_b32 v151, v141, v150
	s_waitcnt lgkmcnt(0)
	v_add_f32_e32 v150, v150, v151
	ds_bpermute_b32 v151, v142, v150
	s_waitcnt lgkmcnt(0)
	v_add_f32_e32 v150, v150, v151
	ds_bpermute_b32 v151, v143, v150
	s_waitcnt lgkmcnt(0)
	v_add_f32_e32 v150, v150, v151
	ds_bpermute_b32 v151, v144, v150
	s_waitcnt lgkmcnt(0)
	v_add_f32_e32 v150, v150, v151
	ds_bpermute_b32 v151, v32, v150
	s_waitcnt lgkmcnt(0)
	v_add_f32_e32 v150, v150, v151
	v_fmamk_f32 v150, v150, 0x3a000000, v33
	v_mul_f32_e32 v156, 0x4f800000, v150
	v_cmp_gt_f32_e32 vcc, s10, v150
	s_nop 1
	v_cndmask_b32_e32 v150, v150, v156, vcc
	v_sqrt_f32_e32 v156, v150
	s_nop 0
	v_add_u32_e32 v152, -1, v156
	v_add_u32_e32 v153, 1, v156
	v_fma_f32 v154, -v152, v156, v150
	v_fma_f32 v155, -v153, v156, v150
	v_cmp_ge_f32_e64 s[6:7], 0, v154
	s_nop 1
	v_cndmask_b32_e64 v156, v156, v152, s[6:7]
	v_cmp_lt_f32_e64 s[6:7], 0, v155
	s_nop 1
	v_cndmask_b32_e64 v156, v156, v153, s[6:7]
	v_mul_f32_e32 v152, 0x37800000, v156
	v_cndmask_b32_e32 v156, v156, v152, vcc
	v_cmp_class_f32_e32 vcc, v150, v34
	s_nop 1
	v_cndmask_b32_e32 v150, v156, v150, vcc
	v_div_scale_f32 v156, s[6:7], v150, v150, 1.0
	v_rcp_f32_e32 v153, v156
	v_div_scale_f32 v152, vcc, 1.0, v150, 1.0
	v_fma_f32 v154, -v156, v153, 1.0
	v_fmac_f32_e32 v153, v154, v153
	v_mul_f32_e32 v154, v152, v153
	v_fma_f32 v155, -v156, v154, v152
	v_fmac_f32_e32 v154, v155, v153
	v_fma_f32 v156, -v156, v154, v152
	v_div_fmas_f32 v156, v156, v153, v154
	v_div_fixup_f32 v156, v156, v150, 1.0
	v_pk_mul_f32 v[204:205], v[156:157], v[0:1] op_sel_hi:[0,1]
	v_pk_mul_f32 v[206:207], v[156:157], v[2:3] op_sel_hi:[0,1]
	v_pk_fma_f32 v[72:73], v[208:209], v[204:205], v[72:73]
	v_pk_fma_f32 v[74:75], v[210:211], v[206:207], v[74:75]
	v_pk_mul_f32 v[204:205], v[156:157], v[4:5] op_sel_hi:[0,1]
	v_pk_mul_f32 v[206:207], v[156:157], v[6:7] op_sel_hi:[0,1]
	v_pk_fma_f32 v[76:77], v[212:213], v[204:205], v[76:77]
	v_pk_fma_f32 v[78:79], v[214:215], v[206:207], v[78:79]
	v_pk_mul_f32 v[204:205], v[156:157], v[8:9] op_sel_hi:[0,1]
	v_pk_mul_f32 v[206:207], v[156:157], v[10:11] op_sel_hi:[0,1]
	v_pk_fma_f32 v[80:81], v[216:217], v[204:205], v[80:81]
	v_pk_fma_f32 v[82:83], v[218:219], v[206:207], v[82:83]
	v_pk_mul_f32 v[204:205], v[156:157], v[12:13] op_sel_hi:[0,1]
	v_pk_mul_f32 v[206:207], v[156:157], v[14:15] op_sel_hi:[0,1]
	v_pk_fma_f32 v[84:85], v[220:221], v[204:205], v[84:85]
	v_pk_fma_f32 v[86:87], v[222:223], v[206:207], v[86:87]
	v_pk_mul_f32 v[204:205], v[156:157], v[16:17] op_sel_hi:[0,1]
	v_pk_mul_f32 v[206:207], v[156:157], v[18:19] op_sel_hi:[0,1]
	v_pk_fma_f32 v[88:89], v[224:225], v[204:205], v[88:89]
	v_pk_fma_f32 v[90:91], v[226:227], v[206:207], v[90:91]
	v_pk_mul_f32 v[204:205], v[156:157], v[20:21] op_sel_hi:[0,1]
	v_pk_mul_f32 v[206:207], v[156:157], v[22:23] op_sel_hi:[0,1]
	v_pk_fma_f32 v[92:93], v[228:229], v[204:205], v[92:93]
	v_pk_fma_f32 v[94:95], v[230:231], v[206:207], v[94:95]
	v_pk_mul_f32 v[204:205], v[156:157], v[24:25] op_sel_hi:[0,1]
	v_pk_mul_f32 v[206:207], v[156:157], v[26:27] op_sel_hi:[0,1]
	v_pk_fma_f32 v[96:97], v[232:233], v[204:205], v[96:97]
	v_pk_fma_f32 v[98:99], v[234:235], v[206:207], v[98:99]
	v_pk_mul_f32 v[204:205], v[156:157], v[28:29] op_sel_hi:[0,1]
	v_pk_mul_f32 v[206:207], v[156:157], v[30:31] op_sel_hi:[0,1]
	v_pk_fma_f32 v[100:101], v[236:237], v[204:205], v[100:101]
	v_pk_fma_f32 v[102:103], v[238:239], v[206:207], v[102:103]
	v_pk_mul_f32 v[146:147], v[72:73], v[72:73]
	v_pk_mul_f32 v[148:149], v[74:75], v[74:75]
	v_pk_fma_f32 v[146:147], v[76:77], v[76:77], v[146:147]
	v_pk_fma_f32 v[148:149], v[78:79], v[78:79], v[148:149]
	v_pk_fma_f32 v[146:147], v[80:81], v[80:81], v[146:147]
	v_pk_fma_f32 v[148:149], v[82:83], v[82:83], v[148:149]
	v_pk_fma_f32 v[146:147], v[84:85], v[84:85], v[146:147]
	v_pk_fma_f32 v[148:149], v[86:87], v[86:87], v[148:149]
	v_pk_fma_f32 v[146:147], v[88:89], v[88:89], v[146:147]
	v_pk_fma_f32 v[148:149], v[90:91], v[90:91], v[148:149]
	v_pk_fma_f32 v[146:147], v[92:93], v[92:93], v[146:147]
	v_pk_fma_f32 v[148:149], v[94:95], v[94:95], v[148:149]
	v_pk_fma_f32 v[146:147], v[96:97], v[96:97], v[146:147]
	v_pk_fma_f32 v[148:149], v[98:99], v[98:99], v[148:149]
	v_pk_fma_f32 v[146:147], v[100:101], v[100:101], v[146:147]
	v_pk_fma_f32 v[148:149], v[102:103], v[102:103], v[148:149]
	v_cvt_pk_bf16_f32 v40, v72, v73
	v_cvt_pk_bf16_f32 v41, v74, v75
	global_store_dwordx2 v162, v[40:41], s[24:25]
	v_cvt_pk_bf16_f32 v42, v76, v77
	v_cvt_pk_bf16_f32 v43, v78, v79
	global_store_dwordx2 v162, v[42:43], s[24:25] offset:512
	v_cvt_pk_bf16_f32 v44, v80, v81
	v_cvt_pk_bf16_f32 v45, v82, v83
	global_store_dwordx2 v162, v[44:45], s[24:25] offset:1024
	v_cvt_pk_bf16_f32 v46, v84, v85
	v_cvt_pk_bf16_f32 v47, v86, v87
	global_store_dwordx2 v162, v[46:47], s[24:25] offset:1536
	v_cvt_pk_bf16_f32 v48, v88, v89
	v_cvt_pk_bf16_f32 v49, v90, v91
	global_store_dwordx2 v162, v[48:49], s[24:25] offset:2048
	v_cvt_pk_bf16_f32 v50, v92, v93
	v_cvt_pk_bf16_f32 v51, v94, v95
	global_store_dwordx2 v162, v[50:51], s[24:25] offset:2560
	v_cvt_pk_bf16_f32 v52, v96, v97
	v_cvt_pk_bf16_f32 v53, v98, v99
	global_store_dwordx2 v162, v[52:53], s[24:25] offset:3072
	v_cvt_pk_bf16_f32 v54, v100, v101
	v_cvt_pk_bf16_f32 v55, v102, v103
	global_store_dwordx2 v162, v[54:55], s[24:25] offset:3584
	v_pk_add_f32 v[146:147], v[146:147], v[148:149]
	s_nop 0
	v_add_f32_e32 v150, v146, v147
	ds_bpermute_b32 v151, v140, v150
	s_waitcnt lgkmcnt(0)
; __device__ __forceinline__ unsigned pk2(float lo, float hi) { const f32x2_h v = {lo, hi}; return __builtin_bit_cast(unsigned, __builtin_convertvector(v, bf16x2_h)); }
; __global__ void __launch_bounds__(512, 2) fwd_megakernel(Params p) {
;     ...
;         const float* gpo = p.in[21];
;         for (int m = gw; m < MROWS; m += NGW) {
;             const u32x2* r8 = (const u32x2*)(MB + (size_t)m * DM) + lane; const f32x4* xr = (const f32x4*)xrow_ptr(p, m) + lane; f32x4 v[8]; float s = 0.f;
; #pragma unroll
;             for (int j = 0; j < 8; ++j) { const u32x2 w = r8[64 * j]; v[j] = (f32x4){__uint_as_float(w.x << 16), __uint_as_float(w.x & 0xffff0000u), __uint_as_float(w.y << 16), __uint_as_float(w.y & 0xffff0000u)};
;                 s += (v[j].x * v[j].x + v[j].y * v[j].y) + (v[j].z * v[j].z + v[j].w * v[j].w); }
;             const float rm = 1.f / sqrtf(wave_sum(s) * (1.f / DM) + RMS_EPS); float s1 = 0.f;
;             u32x2* h8 = (u32x2*)(Hb + (size_t)m * DM) + lane;
; #pragma unroll
;             for (int j = 0; j < 8; ++j) { const f32x4 gg = *(const f32x4*)(gpo + 4 * lane + 256 * j); v[j] = xr[64 * j] + v[j] * rm * gg;
;                 s1 += (v[j].x * v[j].x + v[j].y * v[j].y) + (v[j].z * v[j].z + v[j].w * v[j].w);
;                 u32x2 o; o.x = pk2(v[j].x, v[j].y); o.y = pk2(v[j].z, v[j].w); h8[64 * j] = o; }
;             s1 = wave_sum(s1);
;             if (lane == 0) rsq_x[m] = s1;
;         }
	v_add_f32_e32 v150, v150, v151
	ds_bpermute_b32 v151, v141, v150
	s_waitcnt lgkmcnt(0)
	v_add_f32_e32 v150, v150, v151
	ds_bpermute_b32 v151, v142, v150
	s_waitcnt lgkmcnt(0)
	v_add_f32_e32 v150, v150, v151
	ds_bpermute_b32 v151, v143, v150
	s_waitcnt lgkmcnt(0)
	v_add_f32_e32 v150, v150, v151
	ds_bpermute_b32 v151, v144, v150
	s_waitcnt lgkmcnt(0)
	v_add_f32_e32 v150, v150, v151
	ds_bpermute_b32 v151, v32, v150
	s_waitcnt lgkmcnt(0)
	v_add_f32_e32 v150, v150, v151
	s_and_saveexec_b64 s[6:7], s[4:5]
	global_store_dword v35, v150, s[26:27]
	s_mov_b64 exec, s[6:7]
	s_cmpk_gt_i32 s14, 0x5fff
	s_cbranch_scc1 .LBB0_835
	s_waitcnt vmcnt(9)
	v_lshlrev_b32_e32 v0, 16, v56
	v_and_b32_e32 v1, 0xffff0000, v56
	v_lshlrev_b32_e32 v2, 16, v57
	v_and_b32_e32 v3, 0xffff0000, v57
	v_lshlrev_b32_e32 v4, 16, v58
	v_and_b32_e32 v5, 0xffff0000, v58
	v_lshlrev_b32_e32 v6, 16, v59
	v_and_b32_e32 v7, 0xffff0000, v59
	v_lshlrev_b32_e32 v8, 16, v60
	v_and_b32_e32 v9, 0xffff0000, v60
	v_lshlrev_b32_e32 v10, 16, v61
	v_and_b32_e32 v11, 0xffff0000, v61
	v_lshlrev_b32_e32 v12, 16, v62
	v_and_b32_e32 v13, 0xffff0000, v62
	v_lshlrev_b32_e32 v14, 16, v63
	v_and_b32_e32 v15, 0xffff0000, v63
	v_lshlrev_b32_e32 v16, 16, v64
	v_and_b32_e32 v17, 0xffff0000, v64
	v_lshlrev_b32_e32 v18, 16, v65
	v_and_b32_e32 v19, 0xffff0000, v65
	v_lshlrev_b32_e32 v20, 16, v66
	v_and_b32_e32 v21, 0xffff0000, v66
	v_lshlrev_b32_e32 v22, 16, v67
	v_and_b32_e32 v23, 0xffff0000, v67
	v_lshlrev_b32_e32 v24, 16, v68
	v_and_b32_e32 v25, 0xffff0000, v68
	v_lshlrev_b32_e32 v26, 16, v69
	v_and_b32_e32 v27, 0xffff0000, v69
	v_lshlrev_b32_e32 v28, 16, v70
	v_and_b32_e32 v29, 0xffff0000, v70
	v_lshlrev_b32_e32 v30, 16, v71
	v_and_b32_e32 v31, 0xffff0000, v71
	s_ashr_i32 s15, s14, 31
	s_lshl_b64 s[8:9], s[14:15], 12
	s_add_u32 s24, s42, s8
	s_addc_u32 s25, s43, s9
	s_lshl_b64 s[8:9], s[14:15], 2
	s_add_u32 s26, s44, s8
	s_addc_u32 s27, s45, s9
	s_add_i32 s14, s14, s62
	s_cmpk_gt_i32 s14, 0x5fff
	s_cbranch_scc1 .Lp8_nopfB
	s_ashr_i32 s7, s14, 31
	s_mov_b32 s6, s14
	s_lshl_b64 s[8:9], s[6:7], 12
	s_add_u32 s16, s40, s8
	s_addc_u32 s17, s41, s9
	s_add_i32 s8, s14, 0xffffe000
	s_cmpk_lt_i32 s14, 0x2000
	s_cselect_b32 s8, s14, s8
	s_cselect_b32 s18, s36, s38
	s_cselect_b32 s19, s37, s39
	s_ashr_i32 s9, s8, 31
	s_lshl_b64 s[8:9], s[8:9], 13
	s_add_u32 s18, s18, s8
	s_addc_u32 s19, s19, s9
	s_add_u32 s20, s18, 0x1000
	s_addc_u32 s21, s19, 0
	global_load_dwordx2 v[40:41], v162, s[16:17]
	global_load_dwordx2 v[42:43], v162, s[16:17] offset:512
	global_load_dwordx2 v[44:45], v162, s[16:17] offset:1024
	global_load_dwordx2 v[46:47], v162, s[16:17] offset:1536
	global_load_dwordx2 v[48:49], v162, s[16:17] offset:2048
	global_load_dwordx2 v[50:51], v162, s[16:17] offset:2560
	global_load_dwordx2 v[52:53], v162, s[16:17] offset:3072
	global_load_dwordx2 v[54:55], v162, s[16:17] offset:3584
	global_load_dwordx4 v[72:75], v160, s[18:19]
	global_load_dwordx4 v[76:79], v160, s[18:19] offset:1024
	global_load_dwordx4 v[80:83], v160, s[18:19] offset:2048
	global_load_dwordx4 v[84:87], v160, s[18:19] offset:3072
	global_load_dwordx4 v[88:91], v160, s[20:21]
	global_load_dwordx4 v[92:95], v160, s[20:21] offset:1024
	global_load_dwordx4 v[96:99], v160, s[20:21] offset:2048
	global_load_dwordx4 v[100:103], v160, s[20:21] offset:3072
.Lp8_nopfB:
	v_pk_mul_f32 v[146:147], v[0:1], v[0:1]
	v_pk_mul_f32 v[148:149], v[2:3], v[2:3]
	v_pk_fma_f32 v[146:147], v[4:5], v[4:5], v[146:147]
	v_pk_fma_f32 v[148:149], v[6:7], v[6:7], v[148:149]
	v_pk_fma_f32 v[146:147], v[8:9], v[8:9], v[146:147]
	v_pk_fma_f32 v[148:149], v[10:11], v[10:11], v[148:149]
	v_pk_fma_f32 v[146:147], v[12:13], v[12:13], v[146:147]
	v_pk_fma_f32 v[148:149], v[14:15], v[14:15], v[148:149]
	v_pk_fma_f32 v[146:147], v[16:17], v[16:17], v[146:147]
	v_pk_fma_f32 v[148:149], v[18:19], v[18:19], v[148:149]
	v_pk_fma_f32 v[146:147], v[20:21], v[20:21], v[146:147]
	v_pk_fma_f32 v[148:149], v[22:23], v[22:23], v[148:149]
	v_pk_fma_f32 v[146:147], v[24:25], v[24:25], v[146:147]
	v_pk_fma_f32 v[148:149], v[26:27], v[26:27], v[148:149]
	v_pk_fma_f32 v[146:147], v[28:29], v[28:29], v[146:147]
	v_pk_fma_f32 v[148:149], v[30:31], v[30:31], v[148:149]
	s_nop 0
	v_pk_add_f32 v[146:147], v[146:147], v[148:149]
	s_nop 0
	v_add_f32_e32 v150, v146, v147
	ds_bpermute_b32 v151, v140, v150
	s_waitcnt lgkmcnt(0)
	v_add_f32_e32 v150, v150, v151
	ds_bpermute_b32 v151, v141, v150
	s_waitcnt lgkmcnt(0)
	v_add_f32_e32 v150, v150, v151
	ds_bpermute_b32 v151, v142, v150
	s_waitcnt lgkmcnt(0)
	v_add_f32_e32 v150, v150, v151
	ds_bpermute_b32 v151, v143, v150
	s_waitcnt lgkmcnt(0)
	v_add_f32_e32 v150, v150, v151
	ds_bpermute_b32 v151, v144, v150
	s_waitcnt lgkmcnt(0)
	v_add_f32_e32 v150, v150, v151
	ds_bpermute_b32 v151, v32, v150
	s_waitcnt lgkmcnt(0)
; __device__ __forceinline__ unsigned pk2(float lo, float hi) { const f32x2_h v = {lo, hi}; return __builtin_bit_cast(unsigned, __builtin_convertvector(v, bf16x2_h)); }
; __global__ void __launch_bounds__(512, 2) fwd_megakernel(Params p) {
;     ...
;             const u32x2* r8 = (const u32x2*)(MB + (size_t)m * DM) + lane; const f32x4* xr = (const f32x4*)xrow_ptr(p, m) + lane; f32x4 v[8]; float s = 0.f;
; #pragma unroll
;             for (int j = 0; j < 8; ++j) { const u32x2 w = r8[64 * j]; v[j] = (f32x4){__uint_as_float(w.x << 16), __uint_as_float(w.x & 0xffff0000u), __uint_as_float(w.y << 16), __uint_as_float(w.y & 0xffff0000u)};
;                 s += (v[j].x * v[j].x + v[j].y * v[j].y) + (v[j].z * v[j].z + v[j].w * v[j].w); }
;             const float rm = 1.f / sqrtf(wave_sum(s) * (1.f / DM) + RMS_EPS); float s1 = 0.f;
;             u32x2* h8 = (u32x2*)(Hb + (size_t)m * DM) + lane;
; #pragma unroll
;             for (int j = 0; j < 8; ++j) { const f32x4 gg = *(const f32x4*)(gpo + 4 * lane + 256 * j); v[j] = xr[64 * j] + v[j] * rm * gg;
;                 s1 += (v[j].x * v[j].x + v[j].y * v[j].y) + (v[j].z * v[j].z + v[j].w * v[j].w);
;                 u32x2 o; o.x = pk2(v[j].x, v[j].y); o.y = pk2(v[j].z, v[j].w); h8[64 * j] = o; }
;             s1 = wave_sum(s1);
;             if (lane == 0) rsq_x[m] = s1;
;         }
	v_add_f32_e32 v150, v150, v151
	v_fmamk_f32 v150, v150, 0x3a000000, v33
	v_mul_f32_e32 v156, 0x4f800000, v150
	v_cmp_gt_f32_e32 vcc, s10, v150
	s_nop 1
	v_cndmask_b32_e32 v150, v150, v156, vcc
	v_sqrt_f32_e32 v156, v150
	s_nop 0
	v_add_u32_e32 v152, -1, v156
	v_add_u32_e32 v153, 1, v156
	v_fma_f32 v154, -v152, v156, v150
	v_fma_f32 v155, -v153, v156, v150
	v_cmp_ge_f32_e64 s[6:7], 0, v154
	s_nop 1
	v_cndmask_b32_e64 v156, v156, v152, s[6:7]
	v_cmp_lt_f32_e64 s[6:7], 0, v155
	s_nop 1
	v_cndmask_b32_e64 v156, v156, v153, s[6:7]
	v_mul_f32_e32 v152, 0x37800000, v156
	v_cndmask_b32_e32 v156, v156, v152, vcc
	v_cmp_class_f32_e32 vcc, v150, v34
	s_nop 1
	v_cndmask_b32_e32 v150, v156, v150, vcc
	v_div_scale_f32 v156, s[6:7], v150, v150, 1.0
	v_rcp_f32_e32 v153, v156
	v_div_scale_f32 v152, vcc, 1.0, v150, 1.0
	v_fma_f32 v154, -v156, v153, 1.0
	v_fmac_f32_e32 v153, v154, v153
	v_mul_f32_e32 v154, v152, v153
	v_fma_f32 v155, -v156, v154, v152
	v_fmac_f32_e32 v154, v155, v153
	v_fma_f32 v156, -v156, v154, v152
	v_div_fmas_f32 v156, v156, v153, v154
	v_div_fixup_f32 v156, v156, v150, 1.0
	v_pk_mul_f32 v[204:205], v[156:157], v[0:1] op_sel_hi:[0,1]
	v_pk_mul_f32 v[206:207], v[156:157], v[2:3] op_sel_hi:[0,1]
	v_pk_fma_f32 v[172:173], v[208:209], v[204:205], v[172:173]
	v_pk_fma_f32 v[174:175], v[210:211], v[206:207], v[174:175]
	v_pk_mul_f32 v[204:205], v[156:157], v[4:5] op_sel_hi:[0,1]
	v_pk_mul_f32 v[206:207], v[156:157], v[6:7] op_sel_hi:[0,1]
	v_pk_fma_f32 v[176:177], v[212:213], v[204:205], v[176:177]
	v_pk_fma_f32 v[178:179], v[214:215], v[206:207], v[178:179]
	v_pk_mul_f32 v[204:205], v[156:157], v[8:9] op_sel_hi:[0,1]
	v_pk_mul_f32 v[206:207], v[156:157], v[10:11] op_sel_hi:[0,1]
	v_pk_fma_f32 v[180:181], v[216:217], v[204:205], v[180:181]
	v_pk_fma_f32 v[182:183], v[218:219], v[206:207], v[182:183]
	v_pk_mul_f32 v[204:205], v[156:157], v[12:13] op_sel_hi:[0,1]
	v_pk_mul_f32 v[206:207], v[156:157], v[14:15] op_sel_hi:[0,1]
	v_pk_fma_f32 v[184:185], v[220:221], v[204:205], v[184:185]
	v_pk_fma_f32 v[186:187], v[222:223], v[206:207], v[186:187]
	v_pk_mul_f32 v[204:205], v[156:157], v[16:17] op_sel_hi:[0,1]
	v_pk_mul_f32 v[206:207], v[156:157], v[18:19] op_sel_hi:[0,1]
	v_pk_fma_f32 v[188:189], v[224:225], v[204:205], v[188:189]
	v_pk_fma_f32 v[190:191], v[226:227], v[206:207], v[190:191]
	v_pk_mul_f32 v[204:205], v[156:157], v[20:21] op_sel_hi:[0,1]
	v_pk_mul_f32 v[206:207], v[156:157], v[22:23] op_sel_hi:[0,1]
	v_pk_fma_f32 v[192:193], v[228:229], v[204:205], v[192:193]
	v_pk_fma_f32 v[194:195], v[230:231], v[206:207], v[194:195]
	v_pk_mul_f32 v[204:205], v[156:157], v[24:25] op_sel_hi:[0,1]
	v_pk_mul_f32 v[206:207], v[156:157], v[26:27] op_sel_hi:[0,1]
	v_pk_fma_f32 v[196:197], v[232:233], v[204:205], v[196:197]
	v_pk_fma_f32 v[198:199], v[234:235], v[206:207], v[198:199]
	v_pk_mul_f32 v[204:205], v[156:157], v[28:29] op_sel_hi:[0,1]
	v_pk_mul_f32 v[206:207], v[156:157], v[30:31] op_sel_hi:[0,1]
	v_pk_fma_f32 v[200:201], v[236:237], v[204:205], v[200:201]
	v_pk_fma_f32 v[202:203], v[238:239], v[206:207], v[202:203]
	v_pk_mul_f32 v[146:147], v[172:173], v[172:173]
	v_pk_mul_f32 v[148:149], v[174:175], v[174:175]
	v_pk_fma_f32 v[146:147], v[176:177], v[176:177], v[146:147]
	v_pk_fma_f32 v[148:149], v[178:179], v[178:179], v[148:149]
	v_pk_fma_f32 v[146:147], v[180:181], v[180:181], v[146:147]
	v_pk_fma_f32 v[148:149], v[182:183], v[182:183], v[148:149]
	v_pk_fma_f32 v[146:147], v[184:185], v[184:185], v[146:147]
	v_pk_fma_f32 v[148:149], v[186:187], v[186:187], v[148:149]
	v_pk_fma_f32 v[146:147], v[188:189], v[188:189], v[146:147]
	v_pk_fma_f32 v[148:149], v[190:191], v[190:191], v[148:149]
	v_pk_fma_f32 v[146:147], v[192:193], v[192:193], v[146:147]
	v_pk_fma_f32 v[148:149], v[194:195], v[194:195], v[148:149]
	v_pk_fma_f32 v[146:147], v[196:197], v[196:197], v[146:147]
	v_pk_fma_f32 v[148:149], v[198:199], v[198:199], v[148:149]
	v_pk_fma_f32 v[146:147], v[200:201], v[200:201], v[146:147]
	v_pk_fma_f32 v[148:149], v[202:203], v[202:203], v[148:149]
	v_cvt_pk_bf16_f32 v56, v172, v173
	v_cvt_pk_bf16_f32 v57, v174, v175
	global_store_dwordx2 v162, v[56:57], s[24:25]
	v_cvt_pk_bf16_f32 v58, v176, v177
	v_cvt_pk_bf16_f32 v59, v178, v179
	global_store_dwordx2 v162, v[58:59], s[24:25] offset:512
	v_cvt_pk_bf16_f32 v60, v180, v181
	v_cvt_pk_bf16_f32 v61, v182, v183
	global_store_dwordx2 v162, v[60:61], s[24:25] offset:1024
	v_cvt_pk_bf16_f32 v62, v184, v185
	v_cvt_pk_bf16_f32 v63, v186, v187
	global_store_dwordx2 v162, v[62:63], s[24:25] offset:1536
	v_cvt_pk_bf16_f32 v64, v188, v189
	v_cvt_pk_bf16_f32 v65, v190, v191
	global_store_dwordx2 v162, v[64:65], s[24:25] offset:2048
	v_cvt_pk_bf16_f32 v66, v192, v193
	v_cvt_pk_bf16_f32 v67, v194, v195
	global_store_dwordx2 v162, v[66:67], s[24:25] offset:2560
	v_cvt_pk_bf16_f32 v68, v196, v197
	v_cvt_pk_bf16_f32 v69, v198, v199
	global_store_dwordx2 v162, v[68:69], s[24:25] offset:3072
	v_cvt_pk_bf16_f32 v70, v200, v201
	v_cvt_pk_bf16_f32 v71, v202, v203
	global_store_dwordx2 v162, v[70:71], s[24:25] offset:3584
	v_pk_add_f32 v[146:147], v[146:147], v[148:149]
	s_nop 0
	v_add_f32_e32 v150, v146, v147
	ds_bpermute_b32 v151, v140, v150
	s_waitcnt lgkmcnt(0)
	v_add_f32_e32 v150, v150, v151
	ds_bpermute_b32 v151, v141, v150
	s_waitcnt lgkmcnt(0)
	v_add_f32_e32 v150, v150, v151
	ds_bpermute_b32 v151, v142, v150
	s_waitcnt lgkmcnt(0)
	v_add_f32_e32 v150, v150, v151
	ds_bpermute_b32 v151, v143, v150
	s_waitcnt lgkmcnt(0)
	v_add_f32_e32 v150, v150, v151
	ds_bpermute_b32 v151, v144, v150
	s_waitcnt lgkmcnt(0)
	v_add_f32_e32 v150, v150, v151
	ds_bpermute_b32 v151, v32, v150
	s_waitcnt lgkmcnt(0)
	v_add_f32_e32 v150, v150, v151
	s_and_saveexec_b64 s[6:7], s[4:5]
	global_store_dword v35, v150, s[26:27]
	s_mov_b64 exec, s[6:7]
	s_cmpk_gt_i32 s14, 0x5fff
	s_cbranch_scc0 .Lp8_topA
